# e18: e15 + in the out_proj epilogue waves 1..7 scale and store half 0 of the tile while wave 0 waits for half 1's row-sum counter (wave 0 stores its share after the barrier)
# speedup vs baseline: 1.0177x; 1.0177x over previous
;     __device__ __forceinline__ void operator()(AccRef acc, const Unit& u, int wr, int wc, int fr, int fq) const {
;         int row0 = u.pm * 256 + wr * 64 + fr; asm volatile("" : "+v"(row0)); int col0 = u.pn * 256 + wc * 32 + 8 * fq; asm volatile("" : "+v"(col0));
;         const float* gate = mod + (size_t)(u.pm >= 32 ? 1 : 0) * 3 * D + 2 * D + col0;
;         f32x4 gv[2][2];
; #pragma unroll
;         for (int bj = 0; bj < 2; ++bj)
; #pragma unroll
;             for (int n = 0; n < 2; ++n) gv[bj][n] = *(const f32x4*)(gate + bj * HALF + n * 4);
; #pragma unroll
;         for (int ai = 0; ai < 2; ++ai)
; #pragma unroll
;             for (int mp = 0; mp < 2; ++mp) { f32x4 xv[2][2][2];
; #pragma unroll
;                 for (int mm = 0; mm < 2; ++mm)
; #pragma unroll
;                     for (int bj = 0; bj < 2; ++bj)
; #pragma unroll
;                         for (int n = 0; n < 2; ++n) xv[mm][bj][n] = ld_nt(x + (size_t)(row0 + ai * HALF + (mp * 2 + mm) * 16) * D + col0 + bj * HALF + n * 4);
;                 __builtin_amdgcn_sched_barrier(0);
; #pragma unroll
;                 for (int mm = 0; mm < 2; ++mm) { const int m = mp * 2 + mm; const int row = row0 + ai * HALF + m * 16; const size_t o = (size_t)row * D + col0; float ss = 0.f;
; #pragma unroll
;                     for (int bj = 0; bj < 2; ++bj) { const f32x4 r0 = xv[mm][bj][0] + gv[bj][0] * acc[ai][bj][m][0], r1 = xv[mm][bj][1] + gv[bj][1] * acc[ai][bj][m][1];
;                         *(u32x4*)(xo + o + bj * HALF) = pack8h(r0, r1);
;                         ss += ((r0[0] * r0[0] + r0[1] * r0[1]) + (r0[2] * r0[2] + r0[3] * r0[3])) + ((r1[0] * r1[0] + r1[1] * r1[1]) + (r1[2] * r1[2] + r1[3] * r1[3])); }
;                     ss += __shfl_xor(ss, 16); ss += __shfl_xor(ss, 32);
;                     if (fq == 0) rowss[(size_t)row * 32 + u.pn * 4 + wc] = ss; } }
; __device__ __forceinline__ void final_rows(int gw, int lane, const f16* xo, float* out, const float* fg, const float* rowss) {
;     ...
;         for (int rr = 0; rr < 4; ++rr) { part[rr] = lane < 32 ? rowss[(size_t)(r0 + rr) * 32 + lane] : 0.f;
; #pragma unroll
;             for (int j = 0; j < 4; ++j) v[rr][j] = *(const u32x4*)(xo + (size_t)(r0 + rr) * D + 512 * j + 8 * lane); }
;         __builtin_amdgcn_sched_barrier(0);
; #pragma unroll
.Lepi_polled_w1:
	buffer_inv sc1
	s_waitcnt vmcnt(0)
	s_mov_b64 exec, -1
	s_branch .Lepi_d2
.Lepi_d1:
	s_mov_b64 s[86:87], s[82:83]
	v_pk_mul_f32 v[140:141], v[140:141], v[204:205] op_sel_hi:[1,0]
	v_pk_mul_f32 v[142:143], v[142:143], v[204:205] op_sel_hi:[1,0]
	v_pk_mul_f32 v[140:141], v[140:141], v[144:145]
	v_pk_mul_f32 v[142:143], v[142:143], v[146:147]
	v_pk_mul_f32 v[136:137], v[136:137], v[204:205] op_sel_hi:[1,0]
	v_pk_mul_f32 v[138:139], v[138:139], v[204:205] op_sel_hi:[1,0]
	v_pk_mul_f32 v[136:137], v[136:137], v[148:149]
	v_pk_mul_f32 v[138:139], v[138:139], v[150:151]
	v_pk_mul_f32 v[132:133], v[132:133], v[204:205] op_sel_hi:[1,0]
	v_pk_mul_f32 v[134:135], v[134:135], v[204:205] op_sel_hi:[1,0]
	v_pk_mul_f32 v[132:133], v[132:133], v[152:153]
	v_pk_mul_f32 v[134:135], v[134:135], v[154:155]
	v_pk_mul_f32 v[128:129], v[128:129], v[204:205] op_sel_hi:[1,0]
	v_pk_mul_f32 v[130:131], v[130:131], v[204:205] op_sel_hi:[1,0]
	v_pk_mul_f32 v[128:129], v[128:129], v[156:157]
	v_pk_mul_f32 v[130:131], v[130:131], v[158:159]
	global_store_dwordx4 v173, v[140:143], s[86:87]
	global_store_dwordx4 v173, v[136:139], s[86:87] offset:16
	global_store_dwordx4 v173, v[132:135], s[86:87] offset:512
	global_store_dwordx4 v173, v[128:131], s[86:87] offset:528
	s_add_u32 s86, s82, 0x20000
	s_addc_u32 s87, s83, 0
	v_pk_mul_f32 v[124:125], v[124:125], v[206:207] op_sel_hi:[1,0]
	v_pk_mul_f32 v[126:127], v[126:127], v[206:207] op_sel_hi:[1,0]
	v_pk_mul_f32 v[124:125], v[124:125], v[144:145]
	v_pk_mul_f32 v[126:127], v[126:127], v[146:147]
	v_pk_mul_f32 v[116:117], v[116:117], v[206:207] op_sel_hi:[1,0]
	v_pk_mul_f32 v[118:119], v[118:119], v[206:207] op_sel_hi:[1,0]
	v_pk_mul_f32 v[116:117], v[116:117], v[148:149]
	v_pk_mul_f32 v[118:119], v[118:119], v[150:151]
	v_pk_mul_f32 v[100:101], v[100:101], v[206:207] op_sel_hi:[1,0]
	v_pk_mul_f32 v[102:103], v[102:103], v[206:207] op_sel_hi:[1,0]
	v_pk_mul_f32 v[100:101], v[100:101], v[152:153]
	v_pk_mul_f32 v[102:103], v[102:103], v[154:155]
	v_pk_mul_f32 v[96:97], v[96:97], v[206:207] op_sel_hi:[1,0]
	v_pk_mul_f32 v[98:99], v[98:99], v[206:207] op_sel_hi:[1,0]
	v_pk_mul_f32 v[96:97], v[96:97], v[156:157]
	v_pk_mul_f32 v[98:99], v[98:99], v[158:159]
	global_store_dwordx4 v173, v[124:127], s[86:87]
	global_store_dwordx4 v173, v[116:119], s[86:87] offset:16
	global_store_dwordx4 v173, v[100:103], s[86:87] offset:512
	global_store_dwordx4 v173, v[96:99], s[86:87] offset:528
	s_add_u32 s86, s82, 0x40000
	s_addc_u32 s87, s83, 0
	v_pk_mul_f32 v[92:93], v[92:93], v[208:209] op_sel_hi:[1,0]
	v_pk_mul_f32 v[94:95], v[94:95], v[208:209] op_sel_hi:[1,0]
	v_pk_mul_f32 v[92:93], v[92:93], v[144:145]
	v_pk_mul_f32 v[94:95], v[94:95], v[146:147]
	v_pk_mul_f32 v[88:89], v[88:89], v[208:209] op_sel_hi:[1,0]
	v_pk_mul_f32 v[90:91], v[90:91], v[208:209] op_sel_hi:[1,0]
	v_pk_mul_f32 v[88:89], v[88:89], v[148:149]
	v_pk_mul_f32 v[90:91], v[90:91], v[150:151]
	v_pk_mul_f32 v[84:85], v[84:85], v[208:209] op_sel_hi:[1,0]
	v_pk_mul_f32 v[86:87], v[86:87], v[208:209] op_sel_hi:[1,0]
	v_pk_mul_f32 v[84:85], v[84:85], v[152:153]
	v_pk_mul_f32 v[86:87], v[86:87], v[154:155]
	v_pk_mul_f32 v[80:81], v[80:81], v[208:209] op_sel_hi:[1,0]
	v_pk_mul_f32 v[82:83], v[82:83], v[208:209] op_sel_hi:[1,0]
	v_pk_mul_f32 v[80:81], v[80:81], v[156:157]
	v_pk_mul_f32 v[82:83], v[82:83], v[158:159]
	global_store_dwordx4 v173, v[92:95], s[86:87]
	global_store_dwordx4 v173, v[88:91], s[86:87] offset:16
	global_store_dwordx4 v173, v[84:87], s[86:87] offset:512
	global_store_dwordx4 v173, v[80:83], s[86:87] offset:528
	s_add_u32 s86, s82, 0x60000
	s_addc_u32 s87, s83, 0
	v_pk_mul_f32 v[76:77], v[76:77], v[210:211] op_sel_hi:[1,0]
	v_pk_mul_f32 v[78:79], v[78:79], v[210:211] op_sel_hi:[1,0]
	v_pk_mul_f32 v[76:77], v[76:77], v[144:145]
	v_pk_mul_f32 v[78:79], v[78:79], v[146:147]
	v_pk_mul_f32 v[72:73], v[72:73], v[210:211] op_sel_hi:[1,0]
	v_pk_mul_f32 v[74:75], v[74:75], v[210:211] op_sel_hi:[1,0]
	v_pk_mul_f32 v[72:73], v[72:73], v[148:149]
	v_pk_mul_f32 v[74:75], v[74:75], v[150:151]
	v_pk_mul_f32 v[68:69], v[68:69], v[210:211] op_sel_hi:[1,0]
	v_pk_mul_f32 v[70:71], v[70:71], v[210:211] op_sel_hi:[1,0]
	v_pk_mul_f32 v[68:69], v[68:69], v[152:153]
	v_pk_mul_f32 v[70:71], v[70:71], v[154:155]
	v_pk_mul_f32 v[64:65], v[64:65], v[210:211] op_sel_hi:[1,0]
	v_pk_mul_f32 v[66:67], v[66:67], v[210:211] op_sel_hi:[1,0]
	v_pk_mul_f32 v[64:65], v[64:65], v[156:157]
	v_pk_mul_f32 v[66:67], v[66:67], v[158:159]
	global_store_dwordx4 v173, v[76:79], s[86:87]
	global_store_dwordx4 v173, v[72:75], s[86:87] offset:16
	global_store_dwordx4 v173, v[68:71], s[86:87] offset:512
	global_store_dwordx4 v173, v[64:67], s[86:87] offset:528
;     __device__ __forceinline__ void operator()(AccRef acc, const Unit& u, int wr, int wc, int fr, int fq) const {
;         int row0 = u.pm * 256 + wr * 64 + fr; asm volatile("" : "+v"(row0)); int col0 = u.pn * 256 + wc * 32 + 8 * fq; asm volatile("" : "+v"(col0));
;         const float* gate = mod + (size_t)(u.pm >= 32 ? 1 : 0) * 3 * D + 2 * D + col0;
;         f32x4 gv[2][2];
; #pragma unroll
;         for (int bj = 0; bj < 2; ++bj)
; #pragma unroll
;             for (int n = 0; n < 2; ++n) gv[bj][n] = *(const f32x4*)(gate + bj * HALF + n * 4);
; #pragma unroll
;         for (int ai = 0; ai < 2; ++ai)
; #pragma unroll
;             for (int mp = 0; mp < 2; ++mp) { f32x4 xv[2][2][2];
; #pragma unroll
;                 for (int mm = 0; mm < 2; ++mm)
; #pragma unroll
;                     for (int bj = 0; bj < 2; ++bj)
; #pragma unroll
;                         for (int n = 0; n < 2; ++n) xv[mm][bj][n] = ld_nt(x + (size_t)(row0 + ai * HALF + (mp * 2 + mm) * 16) * D + col0 + bj * HALF + n * 4);
;                 __builtin_amdgcn_sched_barrier(0);
; #pragma unroll
;                 for (int mm = 0; mm < 2; ++mm) { const int m = mp * 2 + mm; const int row = row0 + ai * HALF + m * 16; const size_t o = (size_t)row * D + col0; float ss = 0.f;
; #pragma unroll
;                     for (int bj = 0; bj < 2; ++bj) { const f32x4 r0 = xv[mm][bj][0] + gv[bj][0] * acc[ai][bj][m][0], r1 = xv[mm][bj][1] + gv[bj][1] * acc[ai][bj][m][1];
;                         *(u32x4*)(xo + o + bj * HALF) = pack8h(r0, r1);
;                         ss += ((r0[0] * r0[0] + r0[1] * r0[1]) + (r0[2] * r0[2] + r0[3] * r0[3])) + ((r1[0] * r1[0] + r1[1] * r1[1]) + (r1[2] * r1[2] + r1[3] * r1[3])); }
;                     ss += __shfl_xor(ss, 16); ss += __shfl_xor(ss, 32);
;                     if (fq == 0) rowss[(size_t)row * 32 + u.pn * 4 + wc] = ss; } }
; __device__ __forceinline__ void final_rows(int gw, int lane, const f16* xo, float* out, const float* fg, const float* rowss) {
;     ...
;         for (int rr = 0; rr < 4; ++rr) { part[rr] = lane < 32 ? rowss[(size_t)(r0 + rr) * 32 + lane] : 0.f;
; #pragma unroll
;             for (int j = 0; j < 4; ++j) v[rr][j] = *(const u32x4*)(xo + (size_t)(r0 + rr) * D + 512 * j + 8 * lane); }
;         __builtin_amdgcn_sched_barrier(0);
; #pragma unroll
.Lepi_d2:
	s_barrier
	s_add_u32 s90, s26, 0x4000
	s_addc_u32 s91, s27, 0
	global_load_dwordx4 v[188:191], v174, s[90:91]
	global_load_dwordx4 v[192:195], v174, s[90:91] offset:16
	s_add_u32 s90, s26, 0x4800
	s_addc_u32 s91, s27, 0
	global_load_dwordx4 v[196:199], v174, s[90:91]
	global_load_dwordx4 v[200:203], v174, s[90:91] offset:16
	s_add_u32 s90, s26, 0x5000
	s_addc_u32 s91, s27, 0
	global_load_dwordx4 v[104:107], v174, s[90:91]
	global_load_dwordx4 v[108:111], v174, s[90:91] offset:16
	s_add_u32 s90, s26, 0x5800
	s_addc_u32 s91, s27, 0
	global_load_dwordx4 v[112:115], v174, s[90:91]
	global_load_dwordx4 v[120:123], v174, s[90:91] offset:16
	s_cmp_lg_u32 s59, 0
	s_cbranch_scc1 .Lepi_e1
	s_mov_b64 s[86:87], s[82:83]
	v_pk_mul_f32 v[140:141], v[140:141], v[204:205] op_sel_hi:[1,0]
	v_pk_mul_f32 v[142:143], v[142:143], v[204:205] op_sel_hi:[1,0]
	v_pk_mul_f32 v[140:141], v[140:141], v[144:145]
	v_pk_mul_f32 v[142:143], v[142:143], v[146:147]
	v_pk_mul_f32 v[136:137], v[136:137], v[204:205] op_sel_hi:[1,0]
	v_pk_mul_f32 v[138:139], v[138:139], v[204:205] op_sel_hi:[1,0]
	v_pk_mul_f32 v[136:137], v[136:137], v[148:149]
	v_pk_mul_f32 v[138:139], v[138:139], v[150:151]
	v_pk_mul_f32 v[132:133], v[132:133], v[204:205] op_sel_hi:[1,0]
	v_pk_mul_f32 v[134:135], v[134:135], v[204:205] op_sel_hi:[1,0]
	v_pk_mul_f32 v[132:133], v[132:133], v[152:153]
	v_pk_mul_f32 v[134:135], v[134:135], v[154:155]
	v_pk_mul_f32 v[128:129], v[128:129], v[204:205] op_sel_hi:[1,0]
	v_pk_mul_f32 v[130:131], v[130:131], v[204:205] op_sel_hi:[1,0]
	v_pk_mul_f32 v[128:129], v[128:129], v[156:157]
	v_pk_mul_f32 v[130:131], v[130:131], v[158:159]
	global_store_dwordx4 v173, v[140:143], s[86:87]
	global_store_dwordx4 v173, v[136:139], s[86:87] offset:16
	global_store_dwordx4 v173, v[132:135], s[86:87] offset:512
	global_store_dwordx4 v173, v[128:131], s[86:87] offset:528
	s_add_u32 s86, s82, 0x20000
	s_addc_u32 s87, s83, 0
	v_pk_mul_f32 v[124:125], v[124:125], v[206:207] op_sel_hi:[1,0]
	v_pk_mul_f32 v[126:127], v[126:127], v[206:207] op_sel_hi:[1,0]
	v_pk_mul_f32 v[124:125], v[124:125], v[144:145]
	v_pk_mul_f32 v[126:127], v[126:127], v[146:147]
	v_pk_mul_f32 v[116:117], v[116:117], v[206:207] op_sel_hi:[1,0]
	v_pk_mul_f32 v[118:119], v[118:119], v[206:207] op_sel_hi:[1,0]
	v_pk_mul_f32 v[116:117], v[116:117], v[148:149]
	v_pk_mul_f32 v[118:119], v[118:119], v[150:151]
	v_pk_mul_f32 v[100:101], v[100:101], v[206:207] op_sel_hi:[1,0]
	v_pk_mul_f32 v[102:103], v[102:103], v[206:207] op_sel_hi:[1,0]
	v_pk_mul_f32 v[100:101], v[100:101], v[152:153]
	v_pk_mul_f32 v[102:103], v[102:103], v[154:155]
	v_pk_mul_f32 v[96:97], v[96:97], v[206:207] op_sel_hi:[1,0]
	v_pk_mul_f32 v[98:99], v[98:99], v[206:207] op_sel_hi:[1,0]
	v_pk_mul_f32 v[96:97], v[96:97], v[156:157]
	v_pk_mul_f32 v[98:99], v[98:99], v[158:159]
	global_store_dwordx4 v173, v[124:127], s[86:87]
	global_store_dwordx4 v173, v[116:119], s[86:87] offset:16
	global_store_dwordx4 v173, v[100:103], s[86:87] offset:512
	global_store_dwordx4 v173, v[96:99], s[86:87] offset:528
	s_add_u32 s86, s82, 0x40000
	s_addc_u32 s87, s83, 0
	v_pk_mul_f32 v[92:93], v[92:93], v[208:209] op_sel_hi:[1,0]
	v_pk_mul_f32 v[94:95], v[94:95], v[208:209] op_sel_hi:[1,0]
	v_pk_mul_f32 v[92:93], v[92:93], v[144:145]
	v_pk_mul_f32 v[94:95], v[94:95], v[146:147]
	v_pk_mul_f32 v[88:89], v[88:89], v[208:209] op_sel_hi:[1,0]
	v_pk_mul_f32 v[90:91], v[90:91], v[208:209] op_sel_hi:[1,0]
	v_pk_mul_f32 v[88:89], v[88:89], v[148:149]
	v_pk_mul_f32 v[90:91], v[90:91], v[150:151]
	v_pk_mul_f32 v[84:85], v[84:85], v[208:209] op_sel_hi:[1,0]
	v_pk_mul_f32 v[86:87], v[86:87], v[208:209] op_sel_hi:[1,0]
	v_pk_mul_f32 v[84:85], v[84:85], v[152:153]
	v_pk_mul_f32 v[86:87], v[86:87], v[154:155]
	v_pk_mul_f32 v[80:81], v[80:81], v[208:209] op_sel_hi:[1,0]
	v_pk_mul_f32 v[82:83], v[82:83], v[208:209] op_sel_hi:[1,0]
	v_pk_mul_f32 v[80:81], v[80:81], v[156:157]
	v_pk_mul_f32 v[82:83], v[82:83], v[158:159]
	global_store_dwordx4 v173, v[92:95], s[86:87]
	global_store_dwordx4 v173, v[88:91], s[86:87] offset:16
	global_store_dwordx4 v173, v[84:87], s[86:87] offset:512
	global_store_dwordx4 v173, v[80:83], s[86:87] offset:528
	s_add_u32 s86, s82, 0x60000
	s_addc_u32 s87, s83, 0
	v_pk_mul_f32 v[76:77], v[76:77], v[210:211] op_sel_hi:[1,0]
	v_pk_mul_f32 v[78:79], v[78:79], v[210:211] op_sel_hi:[1,0]
	v_pk_mul_f32 v[76:77], v[76:77], v[144:145]
	v_pk_mul_f32 v[78:79], v[78:79], v[146:147]
	v_pk_mul_f32 v[72:73], v[72:73], v[210:211] op_sel_hi:[1,0]
	v_pk_mul_f32 v[74:75], v[74:75], v[210:211] op_sel_hi:[1,0]
	v_pk_mul_f32 v[72:73], v[72:73], v[148:149]
	v_pk_mul_f32 v[74:75], v[74:75], v[150:151]
	v_pk_mul_f32 v[68:69], v[68:69], v[210:211] op_sel_hi:[1,0]
	v_pk_mul_f32 v[70:71], v[70:71], v[210:211] op_sel_hi:[1,0]
	v_pk_mul_f32 v[68:69], v[68:69], v[152:153]
	v_pk_mul_f32 v[70:71], v[70:71], v[154:155]
	v_pk_mul_f32 v[64:65], v[64:65], v[210:211] op_sel_hi:[1,0]
	v_pk_mul_f32 v[66:67], v[66:67], v[210:211] op_sel_hi:[1,0]
	v_pk_mul_f32 v[64:65], v[64:65], v[156:157]
	v_pk_mul_f32 v[66:67], v[66:67], v[158:159]
	global_store_dwordx4 v173, v[76:79], s[86:87]
	global_store_dwordx4 v173, v[72:75], s[86:87] offset:16
	global_store_dwordx4 v173, v[68:71], s[86:87] offset:512
	global_store_dwordx4 v173, v[64:67], s[86:87] offset:528
	s_waitcnt vmcnt(16)
	s_branch .Lepi_e2

;     __device__ __forceinline__ void operator()(AccRef acc, const Unit& u, int wr, int wc, int fr, int fq) const {
;         int row0 = u.pm * 256 + wr * 64 + fr; asm volatile("" : "+v"(row0)); int col0 = u.pn * 256 + wc * 32 + 8 * fq; asm volatile("" : "+v"(col0));
;         const float* gate = mod + (size_t)(u.pm >= 32 ? 1 : 0) * 3 * D + 2 * D + col0;
;         f32x4 gv[2][2];
; #pragma unroll
;         for (int bj = 0; bj < 2; ++bj)
; #pragma unroll
;             for (int n = 0; n < 2; ++n) gv[bj][n] = *(const f32x4*)(gate + bj * HALF + n * 4);
; #pragma unroll
;         for (int ai = 0; ai < 2; ++ai)
; #pragma unroll
;             for (int mp = 0; mp < 2; ++mp) { f32x4 xv[2][2][2];
; #pragma unroll
;                 for (int mm = 0; mm < 2; ++mm)
; #pragma unroll
;                     for (int bj = 0; bj < 2; ++bj)
; #pragma unroll
;                         for (int n = 0; n < 2; ++n) xv[mm][bj][n] = ld_nt(x + (size_t)(row0 + ai * HALF + (mp * 2 + mm) * 16) * D + col0 + bj * HALF + n * 4);
;                 __builtin_amdgcn_sched_barrier(0);
; #pragma unroll
;                 for (int mm = 0; mm < 2; ++mm) { const int m = mp * 2 + mm; const int row = row0 + ai * HALF + m * 16; const size_t o = (size_t)row * D + col0; float ss = 0.f;
; #pragma unroll
;                     for (int bj = 0; bj < 2; ++bj) { const f32x4 r0 = xv[mm][bj][0] + gv[bj][0] * acc[ai][bj][m][0], r1 = xv[mm][bj][1] + gv[bj][1] * acc[ai][bj][m][1];
;                         *(u32x4*)(xo + o + bj * HALF) = pack8h(r0, r1);
;                         ss += ((r0[0] * r0[0] + r0[1] * r0[1]) + (r0[2] * r0[2] + r0[3] * r0[3])) + ((r1[0] * r1[0] + r1[1] * r1[1]) + (r1[2] * r1[2] + r1[3] * r1[3])); }
;                     ss += __shfl_xor(ss, 16); ss += __shfl_xor(ss, 32);
;                     if (fq == 0) rowss[(size_t)row * 32 + u.pn * 4 + wc] = ss; } }
; __device__ __forceinline__ void final_rows(int gw, int lane, const f16* xo, float* out, const float* fg, const float* rowss) {
;     ...
;         for (int rr = 0; rr < 4; ++rr) { part[rr] = lane < 32 ? rowss[(size_t)(r0 + rr) * 32 + lane] : 0.f;
; #pragma unroll
;             for (int j = 0; j < 4; ++j) v[rr][j] = *(const u32x4*)(xo + (size_t)(r0 + rr) * D + 512 * j + 8 * lane); }
;         __builtin_amdgcn_sched_barrier(0);
; #pragma unroll
.Lepi_e2:
	v_pk_add_f32 v[188:189], v[188:189], v[190:191]
	v_pk_add_f32 v[192:193], v[192:193], v[194:195]
	v_pk_add_f32 v[188:189], v[188:189], v[192:193]
	v_add_f32_e32 v188, v188, v189
	v_pk_add_f32 v[196:197], v[196:197], v[198:199]
	v_pk_add_f32 v[200:201], v[200:201], v[202:203]
	v_pk_add_f32 v[196:197], v[196:197], v[200:201]
	v_add_f32_e32 v196, v196, v197
	v_pk_add_f32 v[104:105], v[104:105], v[106:107]
	v_pk_add_f32 v[108:109], v[108:109], v[110:111]
	v_pk_add_f32 v[104:105], v[104:105], v[108:109]
	v_add_f32_e32 v104, v104, v105
	v_pk_add_f32 v[112:113], v[112:113], v[114:115]
	v_pk_add_f32 v[120:121], v[120:121], v[122:123]
	v_pk_add_f32 v[112:113], v[112:113], v[120:121]
	v_add_f32_e32 v112, v112, v113
	ds_bpermute_b32 v214, v186, v188
	ds_bpermute_b32 v215, v186, v196
	ds_bpermute_b32 v216, v186, v104
	ds_bpermute_b32 v217, v186, v112
	s_waitcnt lgkmcnt(0)
	v_add_f32_e32 v188, v188, v214
	v_add_f32_e32 v196, v196, v215
	v_add_f32_e32 v104, v104, v216
	v_add_f32_e32 v112, v112, v217
	ds_bpermute_b32 v214, v185, v188
	ds_bpermute_b32 v215, v185, v196
	ds_bpermute_b32 v216, v185, v104
	ds_bpermute_b32 v217, v185, v112
	s_waitcnt lgkmcnt(0)
	v_add_f32_e32 v188, v188, v214
	v_add_f32_e32 v196, v196, v215
	v_add_f32_e32 v104, v104, v216
	v_add_f32_e32 v112, v112, v217
	v_mov_b32_e32 v214, s95
	v_mov_b32_e32 v215, s95
	v_mov_b32_e32 v216, s95
	v_mov_b32_e32 v217, s95
	v_fmac_f32_e32 v214, s94, v188
	v_fmac_f32_e32 v215, s94, v196
	v_fmac_f32_e32 v216, s94, v104
	v_fmac_f32_e32 v217, s94, v112
	v_rsq_f32_e32 v204, v214
	v_rsq_f32_e32 v206, v215
	v_rsq_f32_e32 v208, v216
	v_rsq_f32_e32 v210, v217
	s_nop 1
	s_add_u32 s86, s82, 0x100000
	s_addc_u32 s87, s83, 0
	v_pk_mul_f32 v[60:61], v[60:61], v[204:205] op_sel_hi:[1,0]
	v_pk_mul_f32 v[62:63], v[62:63], v[204:205] op_sel_hi:[1,0]
	v_pk_mul_f32 v[60:61], v[60:61], v[144:145]
	v_pk_mul_f32 v[62:63], v[62:63], v[146:147]
	v_pk_mul_f32 v[56:57], v[56:57], v[204:205] op_sel_hi:[1,0]
	v_pk_mul_f32 v[58:59], v[58:59], v[204:205] op_sel_hi:[1,0]
	v_pk_mul_f32 v[56:57], v[56:57], v[148:149]
	v_pk_mul_f32 v[58:59], v[58:59], v[150:151]
	v_pk_mul_f32 v[52:53], v[52:53], v[204:205] op_sel_hi:[1,0]
	v_pk_mul_f32 v[54:55], v[54:55], v[204:205] op_sel_hi:[1,0]
	v_pk_mul_f32 v[52:53], v[52:53], v[152:153]
	v_pk_mul_f32 v[54:55], v[54:55], v[154:155]
	v_pk_mul_f32 v[48:49], v[48:49], v[204:205] op_sel_hi:[1,0]
	v_pk_mul_f32 v[50:51], v[50:51], v[204:205] op_sel_hi:[1,0]
	v_pk_mul_f32 v[48:49], v[48:49], v[156:157]
	v_pk_mul_f32 v[50:51], v[50:51], v[158:159]
	global_store_dwordx4 v173, v[60:63], s[86:87]
	global_store_dwordx4 v173, v[56:59], s[86:87] offset:16
	global_store_dwordx4 v173, v[52:55], s[86:87] offset:512
	global_store_dwordx4 v173, v[48:51], s[86:87] offset:528
	s_add_u32 s86, s82, 0x120000
	s_addc_u32 s87, s83, 0
	v_pk_mul_f32 v[44:45], v[44:45], v[206:207] op_sel_hi:[1,0]
	v_pk_mul_f32 v[46:47], v[46:47], v[206:207] op_sel_hi:[1,0]
	v_pk_mul_f32 v[44:45], v[44:45], v[144:145]
	v_pk_mul_f32 v[46:47], v[46:47], v[146:147]
	v_pk_mul_f32 v[40:41], v[40:41], v[206:207] op_sel_hi:[1,0]
	v_pk_mul_f32 v[42:43], v[42:43], v[206:207] op_sel_hi:[1,0]
	v_pk_mul_f32 v[40:41], v[40:41], v[148:149]
	v_pk_mul_f32 v[42:43], v[42:43], v[150:151]
	v_pk_mul_f32 v[36:37], v[36:37], v[206:207] op_sel_hi:[1,0]
	v_pk_mul_f32 v[38:39], v[38:39], v[206:207] op_sel_hi:[1,0]
	v_pk_mul_f32 v[36:37], v[36:37], v[152:153]
	v_pk_mul_f32 v[38:39], v[38:39], v[154:155]
	v_pk_mul_f32 v[32:33], v[32:33], v[206:207] op_sel_hi:[1,0]
	v_pk_mul_f32 v[34:35], v[34:35], v[206:207] op_sel_hi:[1,0]
	v_pk_mul_f32 v[32:33], v[32:33], v[156:157]
	v_pk_mul_f32 v[34:35], v[34:35], v[158:159]
	global_store_dwordx4 v173, v[44:47], s[86:87]
	global_store_dwordx4 v173, v[40:43], s[86:87] offset:16
	global_store_dwordx4 v173, v[36:39], s[86:87] offset:512
	global_store_dwordx4 v173, v[32:35], s[86:87] offset:528
	s_add_u32 s86, s82, 0x140000
	s_addc_u32 s87, s83, 0
	v_pk_mul_f32 v[28:29], v[28:29], v[208:209] op_sel_hi:[1,0]
	v_pk_mul_f32 v[30:31], v[30:31], v[208:209] op_sel_hi:[1,0]
	v_pk_mul_f32 v[28:29], v[28:29], v[144:145]
	v_pk_mul_f32 v[30:31], v[30:31], v[146:147]
	v_pk_mul_f32 v[24:25], v[24:25], v[208:209] op_sel_hi:[1,0]
	v_pk_mul_f32 v[26:27], v[26:27], v[208:209] op_sel_hi:[1,0]
	v_pk_mul_f32 v[24:25], v[24:25], v[148:149]
	v_pk_mul_f32 v[26:27], v[26:27], v[150:151]
	v_pk_mul_f32 v[20:21], v[20:21], v[208:209] op_sel_hi:[1,0]
	v_pk_mul_f32 v[22:23], v[22:23], v[208:209] op_sel_hi:[1,0]
	v_pk_mul_f32 v[20:21], v[20:21], v[152:153]
	v_pk_mul_f32 v[22:23], v[22:23], v[154:155]
	v_pk_mul_f32 v[16:17], v[16:17], v[208:209] op_sel_hi:[1,0]
	v_pk_mul_f32 v[18:19], v[18:19], v[208:209] op_sel_hi:[1,0]
	v_pk_mul_f32 v[16:17], v[16:17], v[156:157]
	v_pk_mul_f32 v[18:19], v[18:19], v[158:159]
	global_store_dwordx4 v173, v[28:31], s[86:87]
	global_store_dwordx4 v173, v[24:27], s[86:87] offset:16
	global_store_dwordx4 v173, v[20:23], s[86:87] offset:512
	global_store_dwordx4 v173, v[16:19], s[86:87] offset:528
	s_add_u32 s86, s82, 0x160000
	s_addc_u32 s87, s83, 0
	v_pk_mul_f32 v[12:13], v[12:13], v[210:211] op_sel_hi:[1,0]
	v_pk_mul_f32 v[14:15], v[14:15], v[210:211] op_sel_hi:[1,0]
	v_pk_mul_f32 v[12:13], v[12:13], v[144:145]
	v_pk_mul_f32 v[14:15], v[14:15], v[146:147]
	v_pk_mul_f32 v[8:9], v[8:9], v[210:211] op_sel_hi:[1,0]
	v_pk_mul_f32 v[10:11], v[10:11], v[210:211] op_sel_hi:[1,0]
	v_pk_mul_f32 v[8:9], v[8:9], v[148:149]
	v_pk_mul_f32 v[10:11], v[10:11], v[150:151]
	v_pk_mul_f32 v[4:5], v[4:5], v[210:211] op_sel_hi:[1,0]
	v_pk_mul_f32 v[6:7], v[6:7], v[210:211] op_sel_hi:[1,0]
	v_pk_mul_f32 v[4:5], v[4:5], v[152:153]
	v_pk_mul_f32 v[6:7], v[6:7], v[154:155]
	v_pk_mul_f32 v[0:1], v[0:1], v[210:211] op_sel_hi:[1,0]
	v_pk_mul_f32 v[2:3], v[2:3], v[210:211] op_sel_hi:[1,0]
	v_pk_mul_f32 v[0:1], v[0:1], v[156:157]
	v_pk_mul_f32 v[2:3], v[2:3], v[158:159]
	global_store_dwordx4 v173, v[12:15], s[86:87]
	global_store_dwordx4 v173, v[8:11], s[86:87] offset:16
	global_store_dwordx4 v173, v[4:7], s[86:87] offset:512
	global_store_dwordx4 v173, v[0:3], s[86:87] offset:528
	s_and_b64 vcc, exec, s[4:5]
	s_cbranch_vccz .Lepi_nopre
	v_lshl_add_u32 v250, s44, 8, v178
	v_lshl_or_b32 v251, s42, 8, v180
	v_readlane_b32 s98, v254, 2
	v_readlane_b32 s99, v254, 3
	v_lshlrev_b32_e32 v250, 13, v250
	v_lshlrev_b32_e32 v251, 2, v251
	s_cmp_gt_i32 s44, 31
	s_cselect_b32 vcc_lo, 0x6000, 0
	s_add_u32 s100, s50, vcc_lo
	s_addc_u32 s101, s51, 0
	s_add_u32 s100, s100, 0x104000
	s_addc_u32 s101, s101, 0
	v_add_u32_e32 v250, v250, v251
	s_nop 1
	global_load_dwordx4 v[218:221], v251, s[100:101]
	global_load_dwordx4 v[222:225], v251, s[100:101] offset:16
	global_load_dwordx4 v[226:229], v251, s[100:101] offset:512
	global_load_dwordx4 v[230:233], v251, s[100:101] offset:528
	global_load_dwordx4 v[234:237], v250, s[98:99] nt
	global_load_dwordx4 v[238:241], v250, s[98:99] offset:16 nt
	global_load_dwordx4 v[242:245], v250, s[98:99] offset:512 nt
	global_load_dwordx4 v[246:249], v250, s[98:99] offset:528 nt
